# v8 + grid barrier: local workgroups spin on the cross-XCD release word directly (no per-XCD release hop)
# speedup vs baseline: 1.0033x; 1.0033x over previous
; __device__ __forceinline__ unsigned xb_ld(unsigned* p)              { return __hip_atomic_load(p, __ATOMIC_RELAXED, __HIP_MEMORY_SCOPE_AGENT); }
; __device__ __forceinline__ unsigned xb_add(unsigned* p, unsigned v) { return __hip_atomic_fetch_add(p, v, __ATOMIC_RELAXED, __HIP_MEMORY_SCOPE_AGENT); }
; #define XB_SPIN(cond, bar) do { unsigned _sp = 0; while (cond) { __builtin_amdgcn_s_sleep(1); \
;     if ((++_sp & 255u) == 0u) { if (xb_ld(&(bar)[XB_TMO])) break; if (_sp > XB_SPIN_CAP) { atomicAdd(&(bar)[XB_TMO], 1u); break; } } } } while (0)
; __device__ __forceinline__ void xcd_barrier(const XcdBarrier& b) {
;     ...
;         const unsigned old = xb_add(&bar[XB_XSUB(b.x)], 1u);
;         const unsigned gen = old / nloc;
;         if (old + 1u == (gen + 1u) * nloc) {
;             __builtin_amdgcn_fence(__ATOMIC_RELEASE, "agent");
;             asm volatile("s_waitcnt vmcnt(0)" ::: "memory");
;             const unsigned og = xb_add(&bar[XB_TOP], 1u);
;             const unsigned tg = og / nx;
;             if (og + 1u == (tg + 1u) * nx) xb_add(&bar[XB_TOPGEN], 1u);
;             else XB_SPIN(xb_ld(&bar[XB_TOPGEN]) == tg, bar);
;             __builtin_amdgcn_fence(__ATOMIC_ACQUIRE, "agent");
;             xb_add(&bar[XB_XGEN(b.x)], 1u);
;             asm volatile("s_waitcnt vmcnt(0)" ::: "memory");
;         } else {
;             XB_SPIN(xb_ld(&bar[XB_XGEN(b.x)]) == gen, bar);
;             __builtin_amdgcn_fence(__ATOMIC_ACQUIRE, "agent");
;             asm volatile("s_waitcnt vmcnt(0)" ::: "memory");
;         }
.LBB0_134:
	s_or_b64 exec, exec, s[6:7]
	s_waitcnt vmcnt(0)
	buffer_inv sc1
	s_waitcnt vmcnt(0)

; __device__ __forceinline__ unsigned xb_add(unsigned* p, unsigned v) { return __hip_atomic_fetch_add(p, v, __ATOMIC_RELAXED, __HIP_MEMORY_SCOPE_AGENT); }
; __device__ __forceinline__ void xcd_barrier(const XcdBarrier& b) {
;     asm volatile("s_waitcnt vmcnt(0)" ::: "memory");
;     __syncthreads();
;     if (threadIdx.x == 0) {
;         unsigned* bar = b.bar;
;         __builtin_amdgcn_s_waitcnt(0);
;         unsigned nloc = b.st[0], nx = b.st[1];
;         if (nloc == 0u) { xcd_barrier_complete(bar, b.x, nloc, nx); b.st[0] = nloc; b.st[1] = nx; }
;         const unsigned old = xb_add(&bar[XB_XSUB(b.x)], 1u);
.LBB0_877:
	v_readlane_b32 s2, v249, 14
	v_readlane_b32 s3, v249, 15
	s_nop 1
	v_mov_b64_e32 v[180:181], s[2:3]
	v_readlane_b32 s2, v249, 26
	s_waitcnt vmcnt(0) expcnt(0) lgkmcnt(0)
	s_nop 0
	v_mov_b32_e32 v1, s2
	ds_read_b32 v3, v1
	v_readlane_b32 s2, v249, 27
	s_waitcnt lgkmcnt(0)
	v_cmp_ne_u32_e32 vcc, 0, v3
	v_mov_b32_e32 v1, s2
	ds_read_b32 v2, v1
	s_cbranch_vccnz .LBB0_892
	s_mov_b32 s2, 1
	s_branch .LBB0_880
